# attention item loop back edge: wave-uniform branch test shortened to s_cmp + s_cbranch_scc1 (all accepted edits stacked)
# baseline (speedup 1.0000x reference)
.LBB0_566:
	s_add_i32 s20, s20, 1
	s_cmp_eq_u32 s20, 3
	s_cbranch_scc1 .LBB0_563
